# attention row-max cross-half exchange: ds_bpermute LDS round trip replaced by v_permlane32_swap (8 sites), on top of E1 + cg-sync removal
# baseline (speedup 1.0000x reference)
; DI void attn_block(const bf16_t* Q, const bf16_t* Kb, const bf16_t* Vt, bf16_t* AO, LAS unsigned char* lds, int bh, int qb, int tid, int wave, int lane) {
;     ...
;             float mx = -1e30f;
; #pragma unroll
;             for (int kb = 0; kb < 2; ++kb)
; #pragma unroll
;                 for (int i = 0; i < 16; ++i) mx = fmaxf(mx, sa[kb][i]);
;             mx = fmaxf(mx, __shfl_xor(mx, 32));
;             if (__any(mx - m > 6.0f)) {
;                 const float mnew = fmaxf(m, mx), alpha = __builtin_amdgcn_exp2f(m - mnew); m = mnew; l *= alpha;
; #pragma unroll
;                 for (int d = 0; d < 4; ++d)
; #pragma unroll
;                     for (int i = 0; i < 16; ++i) o[d][i] *= alpha;
;             }
.LBB0_428:
	v_max3_f32 v206, v80, s23, v81
	v_max3_f32 v206, v206, v82, v83
	v_max3_f32 v206, v206, v84, v85
	v_max3_f32 v206, v206, v86, v87
	v_max3_f32 v206, v206, v88, v89
	v_max3_f32 v206, v206, v90, v91
	v_max3_f32 v206, v206, v92, v93
	v_max3_f32 v206, v206, v94, v95
	s_nop 0
	v_max3_f32 v206, v206, v96, v97
	v_max3_f32 v206, v206, v98, v99
	v_max3_f32 v206, v206, v100, v101
	v_max3_f32 v206, v206, v102, v103
	v_max3_f32 v206, v206, v104, v105
	v_max3_f32 v206, v206, v106, v107
	v_max3_f32 v206, v206, v108, v109
	v_max3_f32 v206, v206, v110, v111
	v_mov_b32_e32 v207, v206
	s_nop 1
	v_permlane32_swap_b32_e32 v206, v207
	s_waitcnt lgkmcnt(0)
	v_max_f32_e32 v207, v207, v207
	v_max_f32_e32 v206, v206, v207
	v_sub_f32_e32 v207, v206, v205
	v_cmp_lt_f32_e32 vcc, s24, v207
	s_cbranch_vccz .LBB0_423
	v_max_f32_e32 v206, v206, v206
	v_max_f32_e32 v207, v205, v205
	v_max_f32_e32 v207, v207, v206
	v_sub_f32_e32 v205, v205, v207
	v_exp_f32_e32 v206, v205
	v_mov_b32_e32 v205, v207
	v_pk_mul_f32 v[78:79], v[78:79], v[206:207] op_sel_hi:[1,0]
	v_pk_mul_f32 v[76:77], v[76:77], v[206:207] op_sel_hi:[1,0]
	v_pk_mul_f32 v[74:75], v[74:75], v[206:207] op_sel_hi:[1,0]
	v_pk_mul_f32 v[72:73], v[72:73], v[206:207] op_sel_hi:[1,0]
	v_pk_mul_f32 v[70:71], v[70:71], v[206:207] op_sel_hi:[1,0]
	v_pk_mul_f32 v[68:69], v[68:69], v[206:207] op_sel_hi:[1,0]
	v_pk_mul_f32 v[66:67], v[66:67], v[206:207] op_sel_hi:[1,0]
	v_pk_mul_f32 v[64:65], v[64:65], v[206:207] op_sel_hi:[1,0]
	v_pk_mul_f32 v[62:63], v[62:63], v[206:207] op_sel_hi:[1,0]
	v_pk_mul_f32 v[60:61], v[60:61], v[206:207] op_sel_hi:[1,0]
	v_pk_mul_f32 v[58:59], v[58:59], v[206:207] op_sel_hi:[1,0]
	v_pk_mul_f32 v[56:57], v[56:57], v[206:207] op_sel_hi:[1,0]
	v_pk_mul_f32 v[54:55], v[54:55], v[206:207] op_sel_hi:[1,0]
	v_pk_mul_f32 v[52:53], v[52:53], v[206:207] op_sel_hi:[1,0]
	v_pk_mul_f32 v[50:51], v[50:51], v[206:207] op_sel_hi:[1,0]
	v_pk_mul_f32 v[48:49], v[48:49], v[206:207] op_sel_hi:[1,0]
	v_pk_mul_f32 v[46:47], v[46:47], v[206:207] op_sel_hi:[1,0]
	v_pk_mul_f32 v[44:45], v[44:45], v[206:207] op_sel_hi:[1,0]
	v_pk_mul_f32 v[42:43], v[42:43], v[206:207] op_sel_hi:[1,0]
	v_pk_mul_f32 v[40:41], v[40:41], v[206:207] op_sel_hi:[1,0]
	v_pk_mul_f32 v[38:39], v[38:39], v[206:207] op_sel_hi:[1,0]
	v_pk_mul_f32 v[36:37], v[36:37], v[206:207] op_sel_hi:[1,0]
	v_pk_mul_f32 v[34:35], v[34:35], v[206:207] op_sel_hi:[1,0]
	v_pk_mul_f32 v[32:33], v[32:33], v[206:207] op_sel_hi:[1,0]
	v_pk_mul_f32 v[30:31], v[30:31], v[206:207] op_sel_hi:[1,0]
	v_pk_mul_f32 v[28:29], v[28:29], v[206:207] op_sel_hi:[1,0]
	v_pk_mul_f32 v[26:27], v[26:27], v[206:207] op_sel_hi:[1,0]
	v_pk_mul_f32 v[24:25], v[24:25], v[206:207] op_sel_hi:[1,0]
	v_pk_mul_f32 v[22:23], v[22:23], v[206:207] op_sel_hi:[1,0]
	v_pk_mul_f32 v[20:21], v[20:21], v[206:207] op_sel_hi:[1,0]
	v_pk_mul_f32 v[18:19], v[18:19], v[206:207] op_sel_hi:[1,0]
	v_pk_mul_f32 v[16:17], v[16:17], v[206:207] op_sel_hi:[1,0]
	v_mul_f32_e32 v204, v204, v206
	s_branch .LBB0_423

; DI void attn_block(const bf16_t* Q, const bf16_t* Kb, const bf16_t* Vt, bf16_t* AO, LAS unsigned char* lds, int bh, int qb, int tid, int wave, int lane) {
;     ...
;             float mx = -1e30f;
; #pragma unroll
;             for (int kb = 0; kb < 2; ++kb)
; #pragma unroll
;                 for (int i = 0; i < 16; ++i) mx = fmaxf(mx, sa[kb][i]);
;             mx = fmaxf(mx, __shfl_xor(mx, 32));
;             if (__any(mx - m > 6.0f)) {
;                 const float mnew = fmaxf(m, mx), alpha = __builtin_amdgcn_exp2f(m - mnew); m = mnew; l *= alpha;
; #pragma unroll
;                 for (int d = 0; d < 4; ++d)
; #pragma unroll
;                     for (int i = 0; i < 16; ++i) o[d][i] *= alpha;
;             }
.LBB0_433:
	v_max3_f32 v1, v80, s23, v81
	v_max3_f32 v1, v1, v82, v83
	v_max3_f32 v1, v1, v84, v85
	v_max3_f32 v1, v1, v86, v87
	v_max3_f32 v1, v1, v88, v89
	v_max3_f32 v1, v1, v90, v91
	v_max3_f32 v1, v1, v92, v93
	v_max3_f32 v1, v1, v94, v95
	s_nop 0
	v_max3_f32 v1, v1, v96, v97
	v_max3_f32 v1, v1, v98, v99
	v_max3_f32 v1, v1, v100, v101
	v_max3_f32 v1, v1, v102, v103
	v_max3_f32 v1, v1, v104, v105
	v_max3_f32 v1, v1, v106, v107
	v_max3_f32 v1, v1, v108, v109
	v_max3_f32 v1, v1, v110, v111
	v_mov_b32_e32 v2, v1
	s_nop 1
	v_permlane32_swap_b32_e32 v1, v2
	s_waitcnt lgkmcnt(0)
	v_max_f32_e32 v2, v2, v2
	v_max_f32_e32 v1, v1, v2
	v_sub_f32_e32 v2, v1, v205
	v_cmp_lt_f32_e32 vcc, s24, v2
	s_cbranch_vccz .LBB0_435
	v_max_f32_e32 v1, v1, v1
	v_max_f32_e32 v2, v205, v205
	v_max_f32_e32 v1, v2, v1
	v_sub_f32_e32 v2, v205, v1
	v_exp_f32_e32 v2, v2
	v_mov_b32_e32 v205, v1
	v_pk_mul_f32 v[78:79], v[78:79], v[2:3] op_sel_hi:[1,0]
	v_pk_mul_f32 v[76:77], v[76:77], v[2:3] op_sel_hi:[1,0]
	v_pk_mul_f32 v[74:75], v[74:75], v[2:3] op_sel_hi:[1,0]
	v_pk_mul_f32 v[72:73], v[72:73], v[2:3] op_sel_hi:[1,0]
	v_pk_mul_f32 v[70:71], v[70:71], v[2:3] op_sel_hi:[1,0]
	v_pk_mul_f32 v[68:69], v[68:69], v[2:3] op_sel_hi:[1,0]
	v_pk_mul_f32 v[66:67], v[66:67], v[2:3] op_sel_hi:[1,0]
	v_pk_mul_f32 v[64:65], v[64:65], v[2:3] op_sel_hi:[1,0]
	v_pk_mul_f32 v[62:63], v[62:63], v[2:3] op_sel_hi:[1,0]
	v_pk_mul_f32 v[60:61], v[60:61], v[2:3] op_sel_hi:[1,0]
	v_pk_mul_f32 v[58:59], v[58:59], v[2:3] op_sel_hi:[1,0]
	v_pk_mul_f32 v[56:57], v[56:57], v[2:3] op_sel_hi:[1,0]
	v_pk_mul_f32 v[54:55], v[54:55], v[2:3] op_sel_hi:[1,0]
	v_pk_mul_f32 v[52:53], v[52:53], v[2:3] op_sel_hi:[1,0]
	v_pk_mul_f32 v[50:51], v[50:51], v[2:3] op_sel_hi:[1,0]
	v_pk_mul_f32 v[48:49], v[48:49], v[2:3] op_sel_hi:[1,0]
	v_pk_mul_f32 v[46:47], v[46:47], v[2:3] op_sel_hi:[1,0]
	v_pk_mul_f32 v[44:45], v[44:45], v[2:3] op_sel_hi:[1,0]
	v_pk_mul_f32 v[42:43], v[42:43], v[2:3] op_sel_hi:[1,0]
	v_pk_mul_f32 v[40:41], v[40:41], v[2:3] op_sel_hi:[1,0]
	v_pk_mul_f32 v[38:39], v[38:39], v[2:3] op_sel_hi:[1,0]
	v_pk_mul_f32 v[36:37], v[36:37], v[2:3] op_sel_hi:[1,0]
	v_pk_mul_f32 v[34:35], v[34:35], v[2:3] op_sel_hi:[1,0]
	v_pk_mul_f32 v[32:33], v[32:33], v[2:3] op_sel_hi:[1,0]
	v_pk_mul_f32 v[30:31], v[30:31], v[2:3] op_sel_hi:[1,0]
	v_pk_mul_f32 v[28:29], v[28:29], v[2:3] op_sel_hi:[1,0]
	v_pk_mul_f32 v[26:27], v[26:27], v[2:3] op_sel_hi:[1,0]
	v_pk_mul_f32 v[24:25], v[24:25], v[2:3] op_sel_hi:[1,0]
	v_pk_mul_f32 v[22:23], v[22:23], v[2:3] op_sel_hi:[1,0]
	v_pk_mul_f32 v[20:21], v[20:21], v[2:3] op_sel_hi:[1,0]
	v_pk_mul_f32 v[18:19], v[18:19], v[2:3] op_sel_hi:[1,0]
	v_pk_mul_f32 v[16:17], v[16:17], v[2:3] op_sel_hi:[1,0]
	v_mul_f32_e32 v204, v204, v2

; DI void attn_block(const bf16_t* Q, const bf16_t* Kb, const bf16_t* Vt, bf16_t* AO, LAS unsigned char* lds, int bh, int qb, int tid, int wave, int lane) {
;     ...
;             float mx = -1e30f;
; #pragma unroll
;             for (int kb = 0; kb < 2; ++kb)
; #pragma unroll
;                 for (int i = 0; i < 16; ++i) mx = fmaxf(mx, sa[kb][i]);
;             mx = fmaxf(mx, __shfl_xor(mx, 32));
;             if (__any(mx - m > 6.0f)) {
;                 const float mnew = fmaxf(m, mx), alpha = __builtin_amdgcn_exp2f(m - mnew); m = mnew; l *= alpha;
; #pragma unroll
;                 for (int d = 0; d < 4; ++d)
; #pragma unroll
;                     for (int i = 0; i < 16; ++i) o[d][i] *= alpha;
;             }
.LBB0_442:
	v_max3_f32 v1, v80, s23, v81
	v_max3_f32 v1, v1, v82, v83
	v_max3_f32 v1, v1, v84, v85
	v_max3_f32 v1, v1, v86, v87
	v_max3_f32 v1, v1, v88, v89
	v_max3_f32 v1, v1, v90, v91
	v_max3_f32 v1, v1, v92, v93
	v_max3_f32 v1, v1, v94, v95
	s_nop 0
	v_max3_f32 v1, v1, v96, v97
	v_max3_f32 v1, v1, v98, v99
	v_max3_f32 v1, v1, v100, v101
	v_max3_f32 v1, v1, v102, v103
	v_max3_f32 v1, v1, v104, v105
	v_max3_f32 v1, v1, v106, v107
	v_max3_f32 v1, v1, v108, v109
	v_max3_f32 v1, v1, v110, v111
	v_mov_b32_e32 v14, v1
	s_nop 1
	v_permlane32_swap_b32_e32 v1, v14
	s_waitcnt lgkmcnt(0)
	v_max_f32_e32 v14, v14, v14
	v_max_f32_e32 v1, v1, v14
	v_sub_f32_e32 v14, v1, v189
	v_cmp_lt_f32_e32 vcc, s24, v14
	s_cbranch_vccz .LBB0_437
	v_max_f32_e32 v1, v1, v1
	v_max_f32_e32 v14, v189, v189
	v_max_f32_e32 v1, v14, v1
	v_sub_f32_e32 v14, v189, v1
	v_exp_f32_e32 v14, v14
	v_mov_b32_e32 v189, v1
	v_pk_mul_f32 v[78:79], v[78:79], v[14:15] op_sel_hi:[1,0]
	v_pk_mul_f32 v[76:77], v[76:77], v[14:15] op_sel_hi:[1,0]
	v_pk_mul_f32 v[74:75], v[74:75], v[14:15] op_sel_hi:[1,0]
	v_pk_mul_f32 v[72:73], v[72:73], v[14:15] op_sel_hi:[1,0]
	v_pk_mul_f32 v[70:71], v[70:71], v[14:15] op_sel_hi:[1,0]
	v_pk_mul_f32 v[68:69], v[68:69], v[14:15] op_sel_hi:[1,0]
	v_pk_mul_f32 v[66:67], v[66:67], v[14:15] op_sel_hi:[1,0]
	v_pk_mul_f32 v[64:65], v[64:65], v[14:15] op_sel_hi:[1,0]
	v_pk_mul_f32 v[62:63], v[62:63], v[14:15] op_sel_hi:[1,0]
	v_pk_mul_f32 v[60:61], v[60:61], v[14:15] op_sel_hi:[1,0]
	v_pk_mul_f32 v[58:59], v[58:59], v[14:15] op_sel_hi:[1,0]
	v_pk_mul_f32 v[56:57], v[56:57], v[14:15] op_sel_hi:[1,0]
	v_pk_mul_f32 v[54:55], v[54:55], v[14:15] op_sel_hi:[1,0]
	v_pk_mul_f32 v[52:53], v[52:53], v[14:15] op_sel_hi:[1,0]
	v_pk_mul_f32 v[50:51], v[50:51], v[14:15] op_sel_hi:[1,0]
	v_pk_mul_f32 v[48:49], v[48:49], v[14:15] op_sel_hi:[1,0]
	v_pk_mul_f32 v[46:47], v[46:47], v[14:15] op_sel_hi:[1,0]
	v_pk_mul_f32 v[44:45], v[44:45], v[14:15] op_sel_hi:[1,0]
	v_pk_mul_f32 v[42:43], v[42:43], v[14:15] op_sel_hi:[1,0]
	v_pk_mul_f32 v[40:41], v[40:41], v[14:15] op_sel_hi:[1,0]
	v_pk_mul_f32 v[38:39], v[38:39], v[14:15] op_sel_hi:[1,0]
	v_pk_mul_f32 v[36:37], v[36:37], v[14:15] op_sel_hi:[1,0]
	v_pk_mul_f32 v[34:35], v[34:35], v[14:15] op_sel_hi:[1,0]
	v_pk_mul_f32 v[32:33], v[32:33], v[14:15] op_sel_hi:[1,0]
	v_pk_mul_f32 v[30:31], v[30:31], v[14:15] op_sel_hi:[1,0]
	v_pk_mul_f32 v[28:29], v[28:29], v[14:15] op_sel_hi:[1,0]
	v_pk_mul_f32 v[26:27], v[26:27], v[14:15] op_sel_hi:[1,0]
	v_pk_mul_f32 v[24:25], v[24:25], v[14:15] op_sel_hi:[1,0]
	v_pk_mul_f32 v[22:23], v[22:23], v[14:15] op_sel_hi:[1,0]
	v_pk_mul_f32 v[20:21], v[20:21], v[14:15] op_sel_hi:[1,0]
	v_pk_mul_f32 v[18:19], v[18:19], v[14:15] op_sel_hi:[1,0]
	v_pk_mul_f32 v[16:17], v[16:17], v[14:15] op_sel_hi:[1,0]
	v_mul_f32_e32 v188, v188, v14
	s_branch .LBB0_437

; DI void attn_block(const bf16_t* Q, const bf16_t* Kb, const bf16_t* Vt, bf16_t* AO, LAS unsigned char* lds, int bh, int qb, int tid, int wave, int lane) {
;     ...
;             float mx = -1e30f;
; #pragma unroll
;             for (int kb = 0; kb < 2; ++kb)
; #pragma unroll
;                 for (int i = 0; i < 16; ++i) mx = fmaxf(mx, sa[kb][i]);
;             mx = fmaxf(mx, __shfl_xor(mx, 32));
;             if (__any(mx - m > 6.0f)) {
;                 const float mnew = fmaxf(m, mx), alpha = __builtin_amdgcn_exp2f(m - mnew); m = mnew; l *= alpha;
; #pragma unroll
;                 for (int d = 0; d < 4; ++d)
; #pragma unroll
;                     for (int i = 0; i < 16; ++i) o[d][i] *= alpha;
;             }
.LBB0_447:
	v_max3_f32 v1, v80, s23, v81
	v_max3_f32 v1, v1, v82, v83
	v_max3_f32 v1, v1, v84, v85
	v_max3_f32 v1, v1, v86, v87
	v_max3_f32 v1, v1, v88, v89
	v_max3_f32 v1, v1, v90, v91
	v_max3_f32 v1, v1, v92, v93
	v_max3_f32 v1, v1, v94, v95
	s_nop 0
	v_max3_f32 v1, v1, v96, v97
	v_max3_f32 v1, v1, v98, v99
	v_max3_f32 v1, v1, v100, v101
	v_max3_f32 v1, v1, v102, v103
	v_max3_f32 v1, v1, v104, v105
	v_max3_f32 v1, v1, v106, v107
	v_max3_f32 v1, v1, v108, v109
	v_max3_f32 v1, v1, v110, v111
	v_mov_b32_e32 v2, v1
	s_nop 1
	v_permlane32_swap_b32_e32 v1, v2
	s_waitcnt lgkmcnt(0)
	v_max_f32_e32 v2, v2, v2
	v_max_f32_e32 v1, v1, v2
	v_sub_f32_e32 v2, v1, v189
	v_cmp_lt_f32_e32 vcc, s24, v2
	s_cbranch_vccz .LBB0_420
	v_max_f32_e32 v1, v1, v1
	v_max_f32_e32 v2, v189, v189
	v_max_f32_e32 v1, v2, v1
	v_sub_f32_e32 v2, v189, v1
	v_exp_f32_e32 v2, v2
	v_mov_b32_e32 v189, v1
	v_pk_mul_f32 v[78:79], v[78:79], v[2:3] op_sel_hi:[1,0]
	v_pk_mul_f32 v[76:77], v[76:77], v[2:3] op_sel_hi:[1,0]
	v_pk_mul_f32 v[74:75], v[74:75], v[2:3] op_sel_hi:[1,0]
	v_pk_mul_f32 v[72:73], v[72:73], v[2:3] op_sel_hi:[1,0]
	v_pk_mul_f32 v[70:71], v[70:71], v[2:3] op_sel_hi:[1,0]
	v_pk_mul_f32 v[68:69], v[68:69], v[2:3] op_sel_hi:[1,0]
	v_pk_mul_f32 v[66:67], v[66:67], v[2:3] op_sel_hi:[1,0]
	v_pk_mul_f32 v[64:65], v[64:65], v[2:3] op_sel_hi:[1,0]
	v_pk_mul_f32 v[62:63], v[62:63], v[2:3] op_sel_hi:[1,0]
	v_pk_mul_f32 v[60:61], v[60:61], v[2:3] op_sel_hi:[1,0]
	v_pk_mul_f32 v[58:59], v[58:59], v[2:3] op_sel_hi:[1,0]
	v_pk_mul_f32 v[56:57], v[56:57], v[2:3] op_sel_hi:[1,0]
	v_pk_mul_f32 v[54:55], v[54:55], v[2:3] op_sel_hi:[1,0]
	v_pk_mul_f32 v[52:53], v[52:53], v[2:3] op_sel_hi:[1,0]
	v_pk_mul_f32 v[50:51], v[50:51], v[2:3] op_sel_hi:[1,0]
	v_pk_mul_f32 v[48:49], v[48:49], v[2:3] op_sel_hi:[1,0]
	v_pk_mul_f32 v[46:47], v[46:47], v[2:3] op_sel_hi:[1,0]
	v_pk_mul_f32 v[44:45], v[44:45], v[2:3] op_sel_hi:[1,0]
	v_pk_mul_f32 v[42:43], v[42:43], v[2:3] op_sel_hi:[1,0]
	v_pk_mul_f32 v[40:41], v[40:41], v[2:3] op_sel_hi:[1,0]
	v_pk_mul_f32 v[38:39], v[38:39], v[2:3] op_sel_hi:[1,0]
	v_pk_mul_f32 v[36:37], v[36:37], v[2:3] op_sel_hi:[1,0]
	v_pk_mul_f32 v[34:35], v[34:35], v[2:3] op_sel_hi:[1,0]
	v_pk_mul_f32 v[32:33], v[32:33], v[2:3] op_sel_hi:[1,0]
	v_pk_mul_f32 v[30:31], v[30:31], v[2:3] op_sel_hi:[1,0]
	v_pk_mul_f32 v[28:29], v[28:29], v[2:3] op_sel_hi:[1,0]
	v_pk_mul_f32 v[26:27], v[26:27], v[2:3] op_sel_hi:[1,0]
	v_pk_mul_f32 v[24:25], v[24:25], v[2:3] op_sel_hi:[1,0]
	v_pk_mul_f32 v[22:23], v[22:23], v[2:3] op_sel_hi:[1,0]
	v_pk_mul_f32 v[20:21], v[20:21], v[2:3] op_sel_hi:[1,0]
	v_pk_mul_f32 v[18:19], v[18:19], v[2:3] op_sel_hi:[1,0]
	v_pk_mul_f32 v[16:17], v[16:17], v[2:3] op_sel_hi:[1,0]
	v_mul_f32_e32 v188, v188, v2
	s_branch .LBB0_420
